# v72 + sample-row LayerNorm (P7 and P10 tails): all eight gamma/beta loads issued with the row loads instead of four serialized load-wait-store steps
# speedup vs baseline: 1.0108x; 1.0024x over previous
; __device__ __forceinline__ float wsum(float v) { v += __shfl_xor(v, 32); v += __shfl_xor(v, 16); v += __shfl_xor(v, 8); v += __shfl_xor(v, 4); v += __shfl_xor(v, 2); v += __shfl_xor(v, 1); return v; }
; __device__ __forceinline__ void sample_rows_ln(unsigned* cnt_s, unsigned* bar, const float* pre, const float* gam, const float* bet, float* of32, bfu* obf, int bid) {
;     ...
;     const int lane = threadIdx.x & 63, wave = threadIdx.x >> 6, row = MP + bid * 8 + wave;
;     const float* pr = pre + (size_t)row * 1024;
;     float4 v[4];
;     float s = 0.f;
; #pragma unroll
;     for (int i = 0; i < 4; ++i) { v[i] = *(const float4*)(pr + i * 256 + lane * 4); s += v[i].x + v[i].y + v[i].z + v[i].w; }
;     const float mu = wsum(s) * (1.f / 1024.f);
;     ...
;     for (int i = 0; i < 4; ++i) {
;         const int c = i * 256 + lane * 4;
;         const float4 gg = *(const float4*)(gam + c), bb = *(const float4*)(bet + c);
.LBB0_1086:
	s_or_b64 exec, exec, s[6:7]
	v_add_u32_e32 v0, s58, v194
	v_add_u32_e32 v2, 0x4000, v0
	v_ashrrev_i32_e32 v3, 31, v2
	v_lshlrev_b32_e32 v0, 2, v172
	v_lshlrev_b64 v[4:5], 12, v[2:3]
	v_and_b32_e32 v46, 0xfc, v0
	v_lshl_add_u64 v[6:7], s[12:13], 0, v[4:5]
	v_lshlrev_b32_e32 v0, 2, v46
	v_mov_b32_e32 v1, 0
	v_lshl_add_u64 v[22:23], v[6:7], 0, v[0:1]
	s_waitcnt lgkmcnt(0)
	s_barrier
	global_load_dwordx4 v[6:9], v[22:23], off
	global_load_dwordx4 v[10:13], v[22:23], off offset:1024
	global_load_dwordx4 v[14:17], v[22:23], off offset:2048
	global_load_dwordx4 v[18:21], v[22:23], off offset:3072
	global_load_dwordx4 v[56:59], v0, s[0:1]
	global_load_dwordx4 v[60:63], v0, s[4:5]
	global_load_dwordx4 v[64:67], v0, s[0:1] offset:1024
	global_load_dwordx4 v[68:71], v0, s[4:5] offset:1024
	global_load_dwordx4 v[72:75], v0, s[0:1] offset:2048
	global_load_dwordx4 v[76:79], v0, s[4:5] offset:2048
	global_load_dwordx4 v[80:83], v0, s[0:1] offset:3072
	global_load_dwordx4 v[84:87], v0, s[4:5] offset:3072
	v_mbcnt_lo_u32_b32 v22, -1, 0
	v_mbcnt_hi_u32_b32 v38, -1, v22
	v_and_b32_e32 v23, 64, v38
	v_xor_b32_e32 v22, 32, v38
	v_add_u32_e32 v39, 64, v23
	v_cmp_lt_i32_e32 vcc, v22, v39
	v_lshl_add_u64 v[4:5], s[66:67], 0, v[4:5]
	s_mov_b32 s3, 0x800000
	v_cndmask_b32_e32 v22, v38, v22, vcc
	v_lshlrev_b32_e32 v47, 2, v22
	v_lshlrev_b64 v[2:3], 11, v[2:3]
	v_lshl_add_u64 v[2:3], s[14:15], 0, v[2:3]
	s_mov_b32 s6, 0x2ce00000
	s_waitcnt vmcnt(11)
	v_mov_b32_e32 v22, v6
	s_waitcnt vmcnt(10)
	v_mov_b32_e32 v23, v10
	v_mov_b32_e32 v24, v7
	v_mov_b32_e32 v25, v11
	v_mov_b32_e32 v26, v8
	v_mov_b32_e32 v27, v12
	v_pk_add_f32 v[22:23], v[22:23], v[24:25]
	v_mov_b32_e32 v28, v9
	v_mov_b32_e32 v29, v13
	s_waitcnt vmcnt(9)
	v_mov_b32_e32 v30, v14
	s_waitcnt vmcnt(8)
	v_mov_b32_e32 v31, v18
	v_mov_b32_e32 v32, v15
	v_mov_b32_e32 v33, v19
	v_pk_add_f32 v[22:23], v[22:23], v[26:27]
	v_mov_b32_e32 v34, v16
	v_mov_b32_e32 v35, v20
	v_pk_add_f32 v[24:25], v[30:31], v[32:33]
	v_pk_add_f32 v[22:23], v[22:23], v[28:29]
	v_mov_b32_e32 v36, v17
	v_mov_b32_e32 v37, v21
	v_pk_add_f32 v[24:25], v[24:25], v[34:35]
	v_add_f32_e32 v22, 0, v22
	v_pk_add_f32 v[24:25], v[24:25], v[36:37]
	v_add_f32_e32 v22, v22, v23
	v_add_f32_e32 v22, v22, v24
	v_add_f32_e32 v22, v22, v25
	ds_bpermute_b32 v23, v47, v22
	v_xor_b32_e32 v24, 16, v38
	v_cmp_lt_i32_e32 vcc, v24, v39
	s_waitcnt lgkmcnt(0)
	v_add_f32_e32 v22, v22, v23
	v_cndmask_b32_e32 v24, v38, v24, vcc
	v_lshlrev_b32_e32 v48, 2, v24
	ds_bpermute_b32 v23, v48, v22
	v_xor_b32_e32 v24, 8, v38
	v_cmp_lt_i32_e32 vcc, v24, v39
	s_waitcnt lgkmcnt(0)
	v_add_f32_e32 v22, v22, v23
	v_cndmask_b32_e32 v24, v38, v24, vcc
	v_lshlrev_b32_e32 v49, 2, v24
	ds_bpermute_b32 v23, v49, v22
	v_xor_b32_e32 v24, 4, v38
	v_cmp_lt_i32_e32 vcc, v24, v39
	s_waitcnt lgkmcnt(0)
	v_add_f32_e32 v22, v22, v23
	v_cndmask_b32_e32 v24, v38, v24, vcc
	v_lshlrev_b32_e32 v50, 2, v24
	ds_bpermute_b32 v23, v50, v22
	v_xor_b32_e32 v24, 2, v38
	v_cmp_lt_i32_e32 vcc, v24, v39
	s_waitcnt lgkmcnt(0)
	v_add_f32_e32 v22, v22, v23
	v_cndmask_b32_e32 v24, v38, v24, vcc
	v_lshlrev_b32_e32 v51, 2, v24
	ds_bpermute_b32 v23, v51, v22
	v_xor_b32_e32 v24, 1, v38
	v_cmp_lt_i32_e32 vcc, v24, v39
	s_waitcnt lgkmcnt(0)
	v_add_f32_e32 v30, v22, v23
	v_cndmask_b32_e32 v24, v38, v24, vcc
	v_lshlrev_b32_e32 v52, 2, v24
	ds_bpermute_b32 v31, v52, v30
	s_waitcnt lgkmcnt(0)
; __device__ __forceinline__ unsigned pk2(float lo, float hi) { f32x2_t v = {lo, hi}; bf16x2_t b = __builtin_convertvector(v, bf16x2_t); return __builtin_bit_cast(unsigned, b); }
; __device__ __forceinline__ float wsum(float v) { v += __shfl_xor(v, 32); v += __shfl_xor(v, 16); v += __shfl_xor(v, 8); v += __shfl_xor(v, 4); v += __shfl_xor(v, 2); v += __shfl_xor(v, 1); return v; }
; __device__ __forceinline__ void sample_rows_ln(unsigned* cnt_s, unsigned* bar, const float* pre, const float* gam, const float* bet, float* of32, bfu* obf, int bid) {
;     ...
;     float q = 0.f;
; #pragma unroll
;     for (int i = 0; i < 4; ++i) { v[i].x -= mu; v[i].y -= mu; v[i].z -= mu; v[i].w -= mu; q += v[i].x * v[i].x + v[i].y * v[i].y + v[i].z * v[i].z + v[i].w * v[i].w; }
;     const float rs = rsqrtf(wsum(q) * (1.f / 1024.f) + EPS);
; #pragma unroll
;     for (int i = 0; i < 4; ++i) {
;         const int c = i * 256 + lane * 4;
;         const float4 gg = *(const float4*)(gam + c), bb = *(const float4*)(bet + c);
;         const float4 y = make_float4(v[i].x * rs * gg.x + bb.x, v[i].y * rs * gg.y + bb.y, v[i].z * rs * gg.z + bb.z, v[i].w * rs * gg.w + bb.w);
;         if (of32) *(float4*)(of32 + (size_t)row * 1024 + c) = y;
;         if (obf) { uint2 o; o.x = pk2(y.x, y.y); o.y = pk2(y.z, y.w); *(uint2*)(obf + (size_t)row * 1024 + c) = o; }
;     }
	v_add_f32_e32 v30, v30, v31
	v_mul_f32_e32 v30, 0x3a800000, v30
	v_pk_add_f32 v[6:7], v[6:7], v[30:31] op_sel_hi:[1,0] neg_lo:[0,1] neg_hi:[0,1]
	v_pk_add_f32 v[10:11], v[10:11], v[30:31] op_sel_hi:[1,0] neg_lo:[0,1] neg_hi:[0,1]
	v_pk_add_f32 v[14:15], v[14:15], v[30:31] op_sel_hi:[1,0] neg_lo:[0,1] neg_hi:[0,1]
	v_pk_add_f32 v[18:19], v[18:19], v[30:31] op_sel_hi:[1,0] neg_lo:[0,1] neg_hi:[0,1]
	v_mov_b32_e32 v32, v7
	v_mov_b32_e32 v33, v11
	v_pk_add_f32 v[8:9], v[8:9], v[30:31] op_sel_hi:[1,0] neg_lo:[0,1] neg_hi:[0,1]
	v_pk_add_f32 v[12:13], v[12:13], v[30:31] op_sel_hi:[1,0] neg_lo:[0,1] neg_hi:[0,1]
	v_pk_add_f32 v[16:17], v[16:17], v[30:31] op_sel_hi:[1,0] neg_lo:[0,1] neg_hi:[0,1]
	v_pk_add_f32 v[20:21], v[20:21], v[30:31] op_sel_hi:[1,0] neg_lo:[0,1] neg_hi:[0,1]
	v_mov_b32_e32 v30, v6
	v_mov_b32_e32 v31, v10
	v_mov_b32_e32 v40, v19
	v_mov_b32_e32 v41, v15
	v_pk_mul_f32 v[32:33], v[32:33], v[32:33]
	v_mov_b32_e32 v34, v8
	v_mov_b32_e32 v35, v12
	v_mov_b32_e32 v38, v18
	v_mov_b32_e32 v39, v14
	v_pk_mul_f32 v[40:41], v[40:41], v[40:41]
	v_pk_fma_f32 v[30:31], v[30:31], v[30:31], v[32:33]
	v_mov_b32_e32 v36, v9
	v_mov_b32_e32 v37, v13
	v_mov_b32_e32 v42, v20
	v_mov_b32_e32 v43, v16
	v_pk_fma_f32 v[32:33], v[38:39], v[38:39], v[40:41]
	v_pk_fma_f32 v[30:31], v[34:35], v[34:35], v[30:31]
	v_mov_b32_e32 v44, v21
	v_mov_b32_e32 v45, v17
	v_pk_fma_f32 v[32:33], v[42:43], v[42:43], v[32:33]
	v_pk_fma_f32 v[30:31], v[36:37], v[36:37], v[30:31]
	v_pk_fma_f32 v[32:33], v[44:45], v[44:45], v[32:33]
	v_add_f32_e32 v30, v30, v31
	v_add_f32_e32 v30, v33, v30
	v_add_f32_e32 v30, v32, v30
	ds_bpermute_b32 v31, v47, v30
	v_mov_b32_e32 v34, 0x3727c5ac
	s_waitcnt lgkmcnt(0)
	v_add_f32_e32 v30, v30, v31
	ds_bpermute_b32 v31, v48, v30
	s_waitcnt lgkmcnt(0)
	v_add_f32_e32 v30, v30, v31
	ds_bpermute_b32 v31, v49, v30
	s_waitcnt lgkmcnt(0)
	v_add_f32_e32 v30, v30, v31
	ds_bpermute_b32 v31, v50, v30
	s_waitcnt lgkmcnt(0)
	v_add_f32_e32 v32, v30, v31
	ds_bpermute_b32 v33, v51, v32
	v_mov_b32_e32 v31, v1
	v_lshlrev_b32_e32 v30, 1, v46
	v_lshl_add_u64 v[30:31], v[2:3], 0, v[30:31]
	s_waitcnt lgkmcnt(0)
	v_add_f32_e32 v35, v32, v33
	ds_bpermute_b32 v36, v52, v35
	v_lshl_add_u64 v[32:33], v[4:5], 0, v[0:1]
	s_waitcnt lgkmcnt(0)
	v_add_f32_e32 v1, v35, v36
	v_fmac_f32_e32 v34, 0x3a800000, v1
	v_mul_f32_e32 v1, 0x4b800000, v34
	v_cmp_gt_f32_e32 vcc, s3, v34
	s_nop 1
	v_cndmask_b32_e32 v1, v34, v1, vcc
	v_rsq_f32_e32 v1, v1
	v_add_co_u32_e64 v34, s[6:7], s6, v32
	v_mul_f32_e32 v2, 0x45800000, v1
	v_cndmask_b32_e32 v36, v1, v2, vcc
	v_pk_mul_f32 v[2:3], v[6:7], v[36:37] op_sel_hi:[1,0]
	v_pk_mul_f32 v[4:5], v[8:9], v[36:37] op_sel_hi:[1,0]
	v_addc_co_u32_e64 v35, s[6:7], 0, v33, s[6:7]
	s_waitcnt vmcnt(0)
	v_mov_b64_e32 v[22:23], v[56:57]
	v_mov_b64_e32 v[24:25], v[58:59]
	v_mov_b64_e32 v[26:27], v[60:61]
	v_mov_b64_e32 v[28:29], v[62:63]
	v_pk_fma_f32 v[2:3], v[22:23], v[2:3], v[26:27]
	v_pk_fma_f32 v[4:5], v[24:25], v[4:5], v[28:29]
	global_store_dwordx4 v[34:35], v[2:5], off
	s_mov_b64 s[6:7], 0x2ce00000
	v_pk_mul_f32 v[10:11], v[10:11], v[36:37] op_sel_hi:[1,0]
	v_cvt_pk_bf16_f32 v2, v2, v3
	v_cvt_pk_bf16_f32 v3, v4, v5
	global_store_dwordx2 v[30:31], v[2:3], off
	v_mov_b64_e32 v[2:3], v[64:65]
	v_mov_b64_e32 v[4:5], v[66:67]
	s_nop 0
	v_mov_b64_e32 v[6:7], v[68:69]
	v_mov_b64_e32 v[8:9], v[70:71]
	v_pk_mul_f32 v[12:13], v[12:13], v[36:37] op_sel_hi:[1,0]
	v_lshl_add_u64 v[22:23], v[32:33], 0, s[6:7]
	v_pk_fma_f32 v[2:3], v[2:3], v[10:11], v[6:7]
	v_pk_fma_f32 v[4:5], v[4:5], v[12:13], v[8:9]
	global_store_dwordx4 v[22:23], v[2:5], off offset:1024
	v_pk_mul_f32 v[10:11], v[14:15], v[36:37] op_sel_hi:[1,0]
	v_pk_mul_f32 v[12:13], v[16:17], v[36:37] op_sel_hi:[1,0]
	v_cvt_pk_bf16_f32 v2, v2, v3
	v_cvt_pk_bf16_f32 v3, v4, v5
	global_store_dwordx2 v[30:31], v[2:3], off offset:512
	v_mov_b64_e32 v[2:3], v[72:73]
	v_mov_b64_e32 v[4:5], v[74:75]
	s_nop 0
	v_mov_b64_e32 v[6:7], v[76:77]
	v_mov_b64_e32 v[8:9], v[78:79]
	v_pk_fma_f32 v[2:3], v[10:11], v[2:3], v[6:7]
	v_pk_fma_f32 v[4:5], v[12:13], v[4:5], v[8:9]
	global_store_dwordx4 v[22:23], v[2:5], off offset:2048
	v_pk_mul_f32 v[10:11], v[20:21], v[36:37] op_sel_hi:[1,0]
	s_nop 0
	v_cvt_pk_bf16_f32 v2, v2, v3
	v_cvt_pk_bf16_f32 v3, v4, v5
	global_store_dwordx2 v[30:31], v[2:3], off offset:1024
	v_mov_b64_e32 v[2:3], v[80:81]
	v_mov_b64_e32 v[4:5], v[82:83]
	s_nop 0
	v_mov_b64_e32 v[6:7], v[84:85]
	v_mov_b64_e32 v[8:9], v[86:87]
	v_pk_mul_f32 v[0:1], v[18:19], v[36:37] op_sel_hi:[1,0]
	v_pk_fma_f32 v[0:1], v[0:1], v[2:3], v[6:7]
	v_pk_fma_f32 v[2:3], v[10:11], v[4:5], v[8:9]
	global_store_dwordx4 v[22:23], v[0:3], off offset:3072
	s_nop 1
	v_cvt_pk_bf16_f32 v0, v0, v1
	v_cvt_pk_bf16_f32 v1, v2, v3
	global_store_dwordx2 v[30:31], v[0:1], off offset:1536

; __device__ __forceinline__ float wsum(float v) { v += __shfl_xor(v, 32); v += __shfl_xor(v, 16); v += __shfl_xor(v, 8); v += __shfl_xor(v, 4); v += __shfl_xor(v, 2); v += __shfl_xor(v, 1); return v; }
; __device__ __forceinline__ void sample_rows_ln(unsigned* cnt_s, unsigned* bar, const float* pre, const float* gam, const float* bet, float* of32, bfu* obf, int bid) {
;     ...
;     const int lane = threadIdx.x & 63, wave = threadIdx.x >> 6, row = MP + bid * 8 + wave;
;     const float* pr = pre + (size_t)row * 1024;
;     float4 v[4];
;     float s = 0.f;
; #pragma unroll
;     for (int i = 0; i < 4; ++i) { v[i] = *(const float4*)(pr + i * 256 + lane * 4); s += v[i].x + v[i].y + v[i].z + v[i].w; }
;     const float mu = wsum(s) * (1.f / 1024.f);
;     float q = 0.f;
; #pragma unroll
;     for (int i = 0; i < 4; ++i) { v[i].x -= mu; v[i].y -= mu; v[i].z -= mu; v[i].w -= mu; q += v[i].x * v[i].x + v[i].y * v[i].y + v[i].z * v[i].z + v[i].w * v[i].w; }
;     const float rs = rsqrtf(wsum(q) * (1.f / 1024.f) + EPS);
.LBB0_1294:
	s_or_b64 exec, exec, s[8:9]
	v_add_u32_e32 v0, s58, v194
	v_add_u32_e32 v2, 0x4000, v0
	v_ashrrev_i32_e32 v3, 31, v2
	v_lshlrev_b64 v[0:1], 12, v[2:3]
	v_lshl_add_u64 v[4:5], s[12:13], 0, v[0:1]
	v_lshlrev_b32_e32 v0, 2, v172
	v_and_b32_e32 v0, 0xfc, v0
	v_mov_b32_e32 v1, 0
	v_lshlrev_b32_e32 v0, 2, v0
	v_lshl_add_u64 v[12:13], v[4:5], 0, v[0:1]
	s_waitcnt lgkmcnt(0)
	s_barrier
	global_load_dwordx4 v[4:7], v[12:13], off
	global_load_dwordx4 v[8:11], v[12:13], off offset:1024
	global_load_dwordx4 v[20:23], v[12:13], off offset:2048
	global_load_dwordx4 v[24:27], v[12:13], off offset:3072
	global_load_dwordx4 v[44:47], v0, s[0:1]
	global_load_dwordx4 v[48:51], v0, s[4:5]
	global_load_dwordx4 v[52:55], v0, s[0:1] offset:1024
	global_load_dwordx4 v[56:59], v0, s[4:5] offset:1024
	global_load_dwordx4 v[60:63], v0, s[0:1] offset:2048
	global_load_dwordx4 v[64:67], v0, s[4:5] offset:2048
	global_load_dwordx4 v[68:71], v0, s[0:1] offset:3072
	global_load_dwordx4 v[72:75], v0, s[4:5] offset:3072
	v_mbcnt_lo_u32_b32 v12, -1, 0
	v_mbcnt_hi_u32_b32 v36, -1, v12
	v_and_b32_e32 v13, 64, v36
	v_xor_b32_e32 v12, 32, v36
	v_add_u32_e32 v37, 64, v13
	v_cmp_lt_i32_e32 vcc, v12, v37
	s_cmp_eq_u64 s[6:7], 0
	s_waitcnt vmcnt(11)
	v_mov_b32_e32 v14, v5
	v_cndmask_b32_e32 v12, v36, v12, vcc
	v_lshlrev_b32_e32 v38, 2, v12
	v_mov_b32_e32 v12, v4
	s_waitcnt vmcnt(10)
	v_mov_b32_e32 v13, v8
	v_mov_b32_e32 v15, v9
	v_mov_b32_e32 v16, v6
	v_mov_b32_e32 v17, v10
	v_pk_add_f32 v[12:13], v[12:13], v[14:15]
	v_mov_b32_e32 v18, v7
	v_mov_b32_e32 v19, v11
	s_waitcnt vmcnt(9)
	v_mov_b32_e32 v28, v20
	s_waitcnt vmcnt(8)
	v_mov_b32_e32 v29, v24
	v_mov_b32_e32 v30, v21
	v_mov_b32_e32 v31, v25
	v_pk_add_f32 v[12:13], v[12:13], v[16:17]
	v_mov_b32_e32 v32, v22
	v_mov_b32_e32 v33, v26
	v_pk_add_f32 v[14:15], v[28:29], v[30:31]
	v_pk_add_f32 v[12:13], v[12:13], v[18:19]
	v_mov_b32_e32 v34, v23
	v_mov_b32_e32 v35, v27
	v_pk_add_f32 v[14:15], v[14:15], v[32:33]
	v_add_f32_e32 v12, 0, v12
	v_pk_add_f32 v[14:15], v[14:15], v[34:35]
	v_add_f32_e32 v12, v12, v13
	v_add_f32_e32 v12, v12, v14
	v_add_f32_e32 v12, v12, v15
	ds_bpermute_b32 v13, v38, v12
	v_xor_b32_e32 v14, 16, v36
	v_cmp_lt_i32_e32 vcc, v14, v37
	s_waitcnt lgkmcnt(0)
	v_add_f32_e32 v12, v12, v13
	v_cndmask_b32_e32 v14, v36, v14, vcc
	v_lshlrev_b32_e32 v39, 2, v14
	ds_bpermute_b32 v13, v39, v12
	v_xor_b32_e32 v14, 8, v36
	v_cmp_lt_i32_e32 vcc, v14, v37
	s_waitcnt lgkmcnt(0)
	v_add_f32_e32 v12, v12, v13
	v_cndmask_b32_e32 v14, v36, v14, vcc
	v_lshlrev_b32_e32 v40, 2, v14
	ds_bpermute_b32 v13, v40, v12
	v_xor_b32_e32 v14, 4, v36
	v_cmp_lt_i32_e32 vcc, v14, v37
	s_waitcnt lgkmcnt(0)
	v_add_f32_e32 v12, v12, v13
	v_cndmask_b32_e32 v14, v36, v14, vcc
	v_lshlrev_b32_e32 v41, 2, v14
	ds_bpermute_b32 v13, v41, v12
	v_xor_b32_e32 v14, 2, v36
	v_cmp_lt_i32_e32 vcc, v14, v37
	s_waitcnt lgkmcnt(0)
	v_add_f32_e32 v12, v12, v13
	v_cndmask_b32_e32 v14, v36, v14, vcc
	v_lshlrev_b32_e32 v42, 2, v14
	ds_bpermute_b32 v13, v42, v12
	v_xor_b32_e32 v14, 1, v36
	v_cmp_lt_i32_e32 vcc, v14, v37
	s_waitcnt lgkmcnt(0)
	v_add_f32_e32 v12, v12, v13
	v_cndmask_b32_e32 v14, v36, v14, vcc
	v_lshlrev_b32_e32 v36, 2, v14
	ds_bpermute_b32 v13, v36, v12
	s_waitcnt lgkmcnt(0)
	v_add_f32_e32 v12, v12, v13
	v_mul_f32_e32 v28, 0x3a800000, v12
	v_pk_add_f32 v[18:19], v[4:5], v[28:29] op_sel_hi:[1,0] neg_lo:[0,1] neg_hi:[0,1]
	v_pk_add_f32 v[14:15], v[8:9], v[28:29] op_sel_hi:[1,0] neg_lo:[0,1] neg_hi:[0,1]
	v_pk_add_f32 v[16:17], v[6:7], v[28:29] op_sel_hi:[1,0] neg_lo:[0,1] neg_hi:[0,1]
	v_pk_add_f32 v[12:13], v[10:11], v[28:29] op_sel_hi:[1,0] neg_lo:[0,1] neg_hi:[0,1]
	v_pk_add_f32 v[10:11], v[20:21], v[28:29] op_sel_hi:[1,0] neg_lo:[0,1] neg_hi:[0,1]
	v_pk_add_f32 v[6:7], v[24:25], v[28:29] op_sel_hi:[1,0] neg_lo:[0,1] neg_hi:[0,1]
	v_pk_mul_f32 v[20:21], v[18:19], v[18:19]
	v_pk_mul_f32 v[24:25], v[14:15], v[14:15]
	v_pk_add_f32 v[8:9], v[22:23], v[28:29] op_sel_hi:[1,0] neg_lo:[0,1] neg_hi:[0,1]
	v_pk_add_f32 v[4:5], v[26:27], v[28:29] op_sel_hi:[1,0] neg_lo:[0,1] neg_hi:[0,1]
	v_pk_mul_f32 v[22:23], v[16:17], v[16:17]
	v_pk_mul_f32 v[26:27], v[12:13], v[12:13]
	v_pk_mul_f32 v[28:29], v[10:11], v[10:11]
	v_add_f32_e32 v24, v24, v25
	v_add_f32_e32 v20, v20, v21
	v_pk_mul_f32 v[30:31], v[8:9], v[8:9]
	v_pk_mul_f32 v[32:33], v[6:7], v[6:7]
	v_add_f32_e32 v21, v28, v29
	v_add_f32_e32 v24, v26, v24
	v_add_f32_e32 v20, v22, v20
	v_pk_mul_f32 v[34:35], v[4:5], v[4:5]
	v_add_f32_e32 v25, v32, v33
	v_add_f32_e32 v21, v30, v21
	v_add_f32_e32 v24, v27, v24
	v_add_f32_e32 v20, v23, v20
	v_add_f32_e32 v22, v34, v25
	v_add_f32_e32 v21, v31, v21
	v_add_f32_e32 v20, v20, v24
	v_add_f32_e32 v20, v21, v20
	v_add_f32_e32 v21, v35, v22
	v_add_f32_e32 v20, v21, v20
	ds_bpermute_b32 v21, v38, v20
	s_waitcnt lgkmcnt(0)
	v_add_f32_e32 v20, v20, v21
	ds_bpermute_b32 v21, v39, v20
	s_waitcnt lgkmcnt(0)
	v_add_f32_e32 v20, v20, v21
	ds_bpermute_b32 v21, v40, v20
	s_waitcnt lgkmcnt(0)
	v_add_f32_e32 v20, v20, v21
	ds_bpermute_b32 v21, v41, v20
	s_waitcnt lgkmcnt(0)
	v_add_f32_e32 v20, v20, v21
	ds_bpermute_b32 v21, v42, v20
	s_waitcnt lgkmcnt(0)
	v_add_f32_e32 v20, v20, v21
	ds_bpermute_b32 v21, v36, v20
	s_cbranch_scc1 .LBB0_1296
; __device__ __forceinline__ unsigned pk2(float lo, float hi) { f32x2_t v = {lo, hi}; bf16x2_t b = __builtin_convertvector(v, bf16x2_t); return __builtin_bit_cast(unsigned, b); }
; __device__ __forceinline__ float wsum(float v) { v += __shfl_xor(v, 32); v += __shfl_xor(v, 16); v += __shfl_xor(v, 8); v += __shfl_xor(v, 4); v += __shfl_xor(v, 2); v += __shfl_xor(v, 1); return v; }
; __device__ __forceinline__ void sample_rows_ln(unsigned* cnt_s, unsigned* bar, const float* pre, const float* gam, const float* bet, float* of32, bfu* obf, int bid) {
;     ...
;     const float rs = rsqrtf(wsum(q) * (1.f / 1024.f) + EPS);
; #pragma unroll
;     for (int i = 0; i < 4; ++i) {
;         const int c = i * 256 + lane * 4;
;         const float4 gg = *(const float4*)(gam + c), bb = *(const float4*)(bet + c);
;         const float4 y = make_float4(v[i].x * rs * gg.x + bb.x, v[i].y * rs * gg.y + bb.y, v[i].z * rs * gg.z + bb.z, v[i].w * rs * gg.w + bb.w);
;         if (of32) *(float4*)(of32 + (size_t)row * 1024 + c) = y;
;         if (obf) { uint2 o; o.x = pk2(y.x, y.y); o.y = pk2(y.z, y.w); *(uint2*)(obf + (size_t)row * 1024 + c) = o; }
	s_waitcnt lgkmcnt(0)
	v_add_f32_e32 v20, v20, v21
	v_mov_b32_e32 v21, 0x3727c5ac
	s_mov_b32 s2, 0x800000
	v_fmac_f32_e32 v21, 0x3a800000, v20
	v_mul_f32_e32 v20, 0x4b800000, v21
	v_cmp_gt_f32_e32 vcc, s2, v21
	v_lshlrev_b64 v[2:3], 10, v[2:3]
	v_lshl_add_u64 v[2:3], v[2:3], 2, s[6:7]
	v_cndmask_b32_e32 v20, v21, v20, vcc
	v_rsq_f32_e32 v20, v20
	v_lshl_add_u64 v[30:31], v[2:3], 0, v[0:1]
	v_mul_f32_e32 v1, 0x45800000, v20
	v_cndmask_b32_e32 v2, v20, v1, vcc
	v_pk_mul_f32 v[18:19], v[18:19], v[2:3] op_sel_hi:[1,0]
	v_pk_mul_f32 v[20:21], v[16:17], v[2:3] op_sel_hi:[1,0]
	v_pk_mul_f32 v[14:15], v[14:15], v[2:3] op_sel_hi:[1,0]
	v_pk_mul_f32 v[10:11], v[10:11], v[2:3] op_sel_hi:[1,0]
	s_waitcnt vmcnt(0)
	v_mov_b64_e32 v[22:23], v[44:45]
	v_mov_b64_e32 v[24:25], v[46:47]
	v_mov_b64_e32 v[26:27], v[48:49]
	v_mov_b64_e32 v[28:29], v[50:51]
	v_pk_fma_f32 v[16:17], v[18:19], v[26:27], v[22:23]
	v_pk_fma_f32 v[18:19], v[20:21], v[28:29], v[24:25]
	global_store_dwordx4 v[30:31], v[16:19], off
	s_nop 1
	v_mov_b64_e32 v[16:17], v[52:53]
	v_mov_b64_e32 v[18:19], v[54:55]
	s_nop 0
	v_mov_b64_e32 v[20:21], v[56:57]
	v_mov_b64_e32 v[22:23], v[58:59]
	v_pk_mul_f32 v[24:25], v[12:13], v[2:3] op_sel_hi:[1,0]
	v_pk_fma_f32 v[12:13], v[14:15], v[20:21], v[16:17]
	v_pk_fma_f32 v[14:15], v[24:25], v[22:23], v[18:19]
	global_store_dwordx4 v[30:31], v[12:15], off offset:1024
	s_nop 1
	v_mov_b64_e32 v[12:13], v[60:61]
	v_mov_b64_e32 v[14:15], v[62:63]
	s_nop 0
	v_mov_b64_e32 v[16:17], v[64:65]
	v_mov_b64_e32 v[18:19], v[66:67]
	v_pk_mul_f32 v[20:21], v[8:9], v[2:3] op_sel_hi:[1,0]
	v_pk_fma_f32 v[8:9], v[10:11], v[16:17], v[12:13]
	v_pk_fma_f32 v[10:11], v[20:21], v[18:19], v[14:15]
	global_store_dwordx4 v[30:31], v[8:11], off offset:2048
	s_nop 1
	v_mov_b64_e32 v[8:9], v[68:69]
	v_mov_b64_e32 v[10:11], v[70:71]
	s_nop 0
	v_mov_b64_e32 v[12:13], v[72:73]
	v_mov_b64_e32 v[14:15], v[74:75]
	v_pk_mul_f32 v[0:1], v[6:7], v[2:3] op_sel_hi:[1,0]
	v_pk_mul_f32 v[2:3], v[4:5], v[2:3] op_sel_hi:[1,0]
	v_pk_fma_f32 v[0:1], v[0:1], v[12:13], v[8:9]
	v_pk_fma_f32 v[2:3], v[2:3], v[14:15], v[10:11]
	global_store_dwordx4 v[30:31], v[0:3], off offset:3072
